# sample attention items that share K/V start a fraction of a microsecond apart
# baseline (speedup 1.0000x reference)
.LBB0_125:
	s_andn2_b64 vcc, exec, s[0:1]
	s_cbranch_vccnz .LBB0_129
	s_and_b32 s0, s25, 15
	s_cmp_eq_u32 s0, 0
	s_cbranch_scc1 .Lattn_nodelay
.Lattn_delay:
	s_sleep 10
	s_add_i32 s0, s0, -1
	s_cmp_lg_u32 s0, 0
	s_cbranch_scc1 .Lattn_delay
.Lattn_nodelay:
	s_add_i32 s0, s25, 0xfffffb80
	s_lshr_b32 s1, s0, 7
	s_bfe_u32 s28, s25, 0x20005
	s_lshl_b32 s0, s1, 2
	s_or_b32 s36, s0, s28
	s_mul_i32 s26, s36, 0x90000
	v_readlane_b32 s4, v254, 49
	s_mul_hi_u32 s0, s36, 0x90000
	s_add_u32 s26, s4, s26
	v_readlane_b32 s4, v254, 50
	s_addc_u32 s27, s4, s0
	s_lshl_b32 s39, s25, 6
	s_lshl_b32 s29, s1, 11
	s_and_b32 s39, s39, 0x7c0
	s_waitcnt vmcnt(2)
	v_mov_b32_e32 v18, v128
	s_or_b32 s29, s29, s39
	s_addk_i32 s29, 0x1000
	v_and_b32_e32 v19, 15, v18
	v_ashrrev_i32_e32 v0, 2, v18
	v_and_b32_e32 v0, -16, v0
	v_or_b32_e32 v1, s29, v19
	v_add_u32_e32 v150, v1, v0
	v_ashrrev_i32_e32 v151, 31, v150
	v_readlane_b32 s4, v254, 41
	v_lshlrev_b64 v[0:1], 10, v[150:151]
	v_readlane_b32 s5, v254, 42
	v_bfe_u32 v2, v18, 4, 2
	s_lshl_b32 s92, s28, 8
	v_lshl_add_u64 v[0:1], s[4:5], 0, v[0:1]
	v_lshl_add_u64 v[0:1], v[0:1], 0, s[92:93]
	v_lshlrev_b32_e32 v130, 4, v2
	v_lshl_add_u64 v[0:1], v[0:1], 0, v[130:131]
	s_mul_i32 s38, s1, 0x240000
	s_lshl_b32 s0, s28, 7
	global_load_dwordx4 v[76:79], v[0:1], off
	global_load_dwordx4 v[72:75], v[0:1], off offset:64
	global_load_dwordx4 v[68:71], v[0:1], off offset:128
	global_load_dwordx4 v[64:67], v[0:1], off offset:192
	v_readlane_b32 s4, v254, 51
	v_ashrrev_i32_e32 v0, 4, v18
	s_mul_hi_u32 s37, s1, 0x240000
	s_add_u32 s28, s4, s38
	v_readlane_b32 s4, v254, 52
	v_ashrrev_i32_e32 v1, 31, v0
	v_lshlrev_b32_e32 v146, 3, v2
	s_addc_u32 s29, s4, s37
	v_ashrrev_i32_e32 v20, 3, v18
	v_lshlrev_b64 v[2:3], 10, v[0:1]
	v_lshlrev_b32_e32 v1, 4, v18
	s_movk_i32 s4, 0x1200
	v_mov_b64_e32 v[10:11], s[26:27]
	v_mad_i64_i32 v[10:11], s[26:27], v20, s4, v[10:11]
	v_and_b32_e32 v12, 0x70, v1
	v_mov_b32_e32 v13, v131
	v_lshl_add_u64 v[10:11], v[10:11], 0, v[12:13]
	s_mov_b32 s26, 0x6c000
	v_add_co_u32_e32 v14, vcc, s26, v10
	s_add_u32 s28, s28, s92
	s_nop 0
	v_addc_co_u32_e32 v15, vcc, 0, v11, vcc
	s_mov_b32 s26, 0x48000
	s_addc_u32 s29, s29, 0
	v_add_co_u32_e32 v16, vcc, s26, v10
	v_lshl_add_u64 v[4:5], s[28:29], 0, v[2:3]
	v_mad_i64_i32 v[8:9], s[28:29], v20, s4, 0
	v_addc_co_u32_e32 v17, vcc, 0, v11, vcc
	s_mov_b32 s4, 0x24000
	v_and_b32_e32 v6, 0xf0, v1
	v_mov_b32_e32 v7, v131
	global_load_dwordx4 v[80:83], v[14:15], off
	global_load_dwordx4 v[84:87], v[16:17], off
	v_add_co_u32_e32 v14, vcc, s4, v10
	v_lshl_add_u64 v[4:5], v[4:5], 0, v[6:7]
	s_nop 0
	v_addc_co_u32_e32 v15, vcc, 0, v11, vcc
	v_add_co_u32_e32 v16, vcc, s21, v4
	s_mov_b32 s4, 0x8000
	s_nop 0
	v_addc_co_u32_e32 v17, vcc, 0, v5, vcc
	global_load_dwordx4 v[92:95], v[14:15], off
	global_load_dwordx4 v[88:91], v[16:17], off
	v_add_co_u32_e32 v14, vcc, s4, v4
	s_movk_i32 s4, 0x4000
	s_nop 0
	v_addc_co_u32_e32 v15, vcc, 0, v5, vcc
	v_add_co_u32_e32 v16, vcc, s4, v4
	s_movk_i32 s4, 0x110
	s_nop 0
	v_addc_co_u32_e32 v17, vcc, 0, v5, vcc
	global_load_dwordx4 v[96:99], v[14:15], off
	global_load_dwordx4 v[104:107], v[16:17], off
	global_load_dwordx4 v[108:111], v[10:11], off
	global_load_dwordx4 v[100:103], v[4:5], off
	v_mul_lo_u32 v1, v0, s4
	v_mad_u64_u32 v[154:155], s[26:27], s36, v220, v[8:9]
	v_and_b32_e32 v0, 7, v18
	s_movk_i32 s4, 0x90
	v_lshl_or_b32 v154, v0, 4, v154
	v_mad_u64_u32 v[156:157], s[26:27], s1, v223, v[2:3]
	v_lshlrev_b32_e32 v0, 4, v19
	v_mul_lo_u32 v4, v20, s4
	v_sub_u32_e32 v5, v130, v146
	v_mul_u32_u24_e32 v7, 0x110, v19
	v_mul_u32_u24_e32 v10, 0x90, v19
	v_or3_b32 v156, v156, s92, v0
	v_mov_b32_e32 v0, 0
	v_lshlrev_b64 v[148:149], 9, v[150:151]
	s_mov_b32 s1, 35
	v_add_u32_e32 v158, v6, v1
	v_add_u32_e32 v151, v12, v4
	v_add_u32_e32 v147, v130, v7
	v_add_u32_e32 v159, v5, v10
	v_mov_b32_e32 v1, v0
	v_mov_b32_e32 v2, v0
	v_mov_b32_e32 v3, v0
	v_mov_b32_e32 v4, v0
	v_mov_b32_e32 v5, v0
	v_mov_b32_e32 v6, v0
	v_mov_b32_e32 v7, v0
	v_mov_b32_e32 v12, v0
	v_mov_b32_e32 v13, v0
	v_mov_b32_e32 v14, v0
	v_mov_b32_e32 v15, v0
	v_mov_b32_e32 v20, v0
	v_mov_b32_e32 v21, v0
	v_mov_b32_e32 v22, v0
	v_mov_b32_e32 v23, v0
	v_mov_b32_e32 v28, v0
	v_mov_b32_e32 v29, v0
	v_mov_b32_e32 v30, v0
	v_mov_b32_e32 v31, v0
	v_mov_b32_e32 v36, v0
	v_mov_b32_e32 v37, v0
	v_mov_b32_e32 v38, v0
	v_mov_b32_e32 v39, v0
	v_mov_b32_e32 v44, v0
	v_mov_b32_e32 v45, v0
	v_mov_b32_e32 v46, v0
	v_mov_b32_e32 v47, v0
	v_mov_b32_e32 v56, v0
	v_mov_b32_e32 v57, v0
	v_mov_b32_e32 v58, v0
	v_mov_b32_e32 v59, v0
	v_mov_b32_e32 v8, v0
	v_mov_b32_e32 v9, v0
	v_mov_b32_e32 v10, v0
	v_mov_b32_e32 v11, v0
	v_mov_b32_e32 v16, v0
	v_mov_b32_e32 v17, v0
	v_mov_b32_e32 v18, v0
	v_mov_b32_e32 v19, v0
	v_mov_b32_e32 v24, v0
	v_mov_b32_e32 v25, v0
	v_mov_b32_e32 v26, v0
	v_mov_b32_e32 v27, v0
	s_waitcnt vmcnt(13)
	v_mov_b32_e32 v32, v0
	v_mov_b32_e32 v33, v0
	v_mov_b32_e32 v34, v0
	v_mov_b32_e32 v35, v0
	v_mov_b32_e32 v40, v0
	v_mov_b32_e32 v41, v0
	v_mov_b32_e32 v42, v0
	v_mov_b32_e32 v43, v0
	v_mov_b32_e32 v48, v0
	v_mov_b32_e32 v49, v0
	v_mov_b32_e32 v50, v0
	v_mov_b32_e32 v51, v0
	v_mov_b32_e32 v52, v0
	v_mov_b32_e32 v53, v0
	v_mov_b32_e32 v54, v0
	v_mov_b32_e32 v55, v0
	v_mov_b32_e32 v60, v0
	v_mov_b32_e32 v61, v0
	v_mov_b32_e32 v62, v0
	v_mov_b32_e32 v63, v0
	v_mov_b32_e32 v152, v0
	v_mov_b32_e32 v153, v0
	s_mov_b64 s[4:5], 0x80
	s_mov_b64 s[6:7], 0x10000
